# baseline (speedup 1.0000x reference)
; __device__ __forceinline__ void run_phase(const Params& p, int ph) {
;     ...
;   } else if (ph == 15) {
;     const int reps = (p.dup & 32) ? 2 : 1;
;     for (int rep = 0; rep < reps; ++rep)
;       for (int c = blockIdx.x; c < 768; c += gridDim.x) {
;         if (EN(256)) hyena_half<0>(p, c, rep + 1 < reps);
;         if (EN(512)) hyena_half<1>(p, c, rep + 1 < reps);
;       }
.LBB0_712:
	s_cmp_eq_u32 s34, 15
	s_cbranch_scc0 .LBB0_1264
	s_bitcmp0_b32 s87, 5
	s_cselect_b32 s66, 1, 2
	s_add_i32 s86, s66, -1
	s_add_u32 s38, s14, 0x161a6000
	s_addc_u32 s74, s15, 0
	s_add_u32 s75, s14, 0x3da6000
	s_addc_u32 s84, s15, 0
	s_add_u32 s43, s14, 0x49a6000
	s_mov_b32 s46, 0
	s_addc_u32 s47, s15, 0
	v_readfirstlane_b32 s98, v208
	s_cmpk_lt_u32 s98, 0x100
	s_cbranch_scc1 .Lhy_prio_skip
	s_setprio 1
.Lhy_prio_skip:
	s_branch .LBB0_715
.LBB0_714:
	s_add_i32 s46, s46, 1
	s_cmp_eq_u32 s46, s66
	s_cbranch_scc1 .LBB0_1264

; __device__ __forceinline__ void run_phase(const Params& p, int ph) {
;     ...
;   } else if (ph == 15) {
;     const int reps = (p.dup & 32) ? 2 : 1;
;     for (int rep = 0; rep < reps; ++rep)
;       for (int c = blockIdx.x; c < 768; c += gridDim.x) {
;         if (EN(256)) hyena_half<0>(p, c, rep + 1 < reps);
;         if (EN(512)) hyena_half<1>(p, c, rep + 1 < reps);
;       }
;   }
.LBB0_1264:
	s_setprio 0
	v_readlane_b32 s4, v255, 14
	v_readlane_b32 s5, v255, 15
	s_branch .LBB0_1269
